# P6 workgroup-group stagger doubled (~20us): K loops of one half under the HBM-bound epilogues of the other
# baseline (speedup 1.0000x reference)
; DI void phase6(const Params& P, char* smem) {
;     ...
;   for (int q = RBLK >> 3; q < 64; q += RGRID >> 3) {
;     const int brow = (q * 2 + ((RBLK & 7) >> 2)) * 256, bcol = (RBLK & 3) * 256;
;     gemm_tile256(cat + (long)brow * 1024, 1024, WoT + (long)bcol * 1024, 1024, 32, smem, [&](int row, int col0, f32x4 v) {
.LBB0_944:
	s_or_b64 exec, exec, s[0:1]
	s_add_u32 s38, s78, 0x8000000
	s_addc_u32 s39, s79, 0
	s_cmp_gt_i32 s75, 63
	s_waitcnt lgkmcnt(0)
	s_barrier
	s_cbranch_scc1 .LBB0_949
	s_bitcmp1_b32 s75, 0
	s_cbranch_scc0 .Lp6_nostagger
	s_sleep 127
	s_sleep 127
	s_sleep 127
	s_sleep 127
	s_sleep 127
	s_sleep 127
